# w_down f32->bf16 conversion moved from P0 into the idle half-round tail of the gate/up GEMM phases (WGs 128-255); plus rsq epilogues
# baseline (speedup 1.0000x reference)
; #define LAS __attribute__((address_space(3)))
; __device__ __forceinline__ void tr_load(const float* W, int N, int item, int lane, float (&wv)[32]) {
;     const int nblk = N / 32, kb = item / nblk, nb = item % nblk, k0 = 64 * kb, n0 = 32 * nb;
; #pragma unroll
;     for (int i = 0; i < 32; ++i) { const int kk = 2 * i + (lane >> 5); wv[i] = __builtin_nontemporal_load(W + (size_t)(k0 + kk) * N + n0 + (lane & 31)); }
; template <int MAP, bool HASG = false, bool PERMW = false>
; __device__ __forceinline__ void transpose_mat(const float* W, int K, int N, bf16_t* WT, LAS float* scr, int gw, int ngw, int lane, const float* gk = nullptr) {
;     const int nitems = (K / 64) * (N / 32);
;     int it = gw;
;     if (it >= nitems) return;
;     float wv[32];
;     tr_load(W, N, it, lane, wv);
.LBB0_36:
	s_cmpk_lt_i32 s6, 0x1600
	v_lshlrev_b32_e32 v0, 2, v133
	v_lshrrev_b32_e32 v138, 3, v132
	s_cselect_b64 s[10:11], -1, 0
	s_cmpk_gt_i32 s6, 0x15ff
	v_and_b32_e32 v48, 0x7c, v0
	v_lshlrev_b32_e32 v139, 2, v138
	v_lshlrev_b32_e32 v140, 6, v138
	s_branch .LBB0_43
	s_add_u32 s12, s7, 0x2c00000
	v_readlane_b32 s56, v254, 60
	s_addc_u32 s13, s25, 0
	s_lshl_b64 s[14:15], s[90:91], 2
	v_readlane_b32 s64, v255, 4
	v_readlane_b32 s65, v255, 5
	s_add_u32 s14, s64, s14
	s_addc_u32 s15, s65, s15
	s_ashr_i32 s16, s6, 31
	s_lshr_b32 s16, s16, 26
	s_add_i32 s16, s6, s16
	s_and_b32 s17, s16, 0xffffffc0
	s_sub_i32 s16, s6, s17
	s_lshl_b32 s16, s16, 5
	v_or_b32_e32 v32, s17, v134
	s_ashr_i32 s17, s16, 31
	s_lshl_b64 s[16:17], s[16:17], 2
	s_add_u32 s16, s14, s16
	v_or_b32_e32 v2, 2, v32
	s_addc_u32 s17, s15, s17
	v_mov_b32_e32 v49, v193
	v_ashrrev_i32_e32 v33, 31, v32
	v_ashrrev_i32_e32 v3, 31, v2
	v_lshl_add_u64 v[34:35], s[16:17], 0, v[48:49]
	v_lshlrev_b64 v[0:1], 13, v[32:33]
	v_lshlrev_b64 v[2:3], 13, v[2:3]
	v_lshl_add_u64 v[0:1], v[34:35], 0, v[0:1]
	v_lshl_add_u64 v[2:3], v[34:35], 0, v[2:3]
	global_load_dword v0, v[0:1], off nt
	v_or_b32_e32 v4, 6, v32
	global_load_dword v1, v[2:3], off nt
	v_or_b32_e32 v2, 4, v32
	v_ashrrev_i32_e32 v3, 31, v2
	v_ashrrev_i32_e32 v5, 31, v4
	v_lshlrev_b64 v[2:3], 13, v[2:3]
	v_lshlrev_b64 v[4:5], 13, v[4:5]
	v_lshl_add_u64 v[2:3], v[34:35], 0, v[2:3]
	v_lshl_add_u64 v[4:5], v[34:35], 0, v[4:5]
	global_load_dword v2, v[2:3], off nt
	v_or_b32_e32 v6, 10, v32
	global_load_dword v3, v[4:5], off nt
	v_or_b32_e32 v4, 8, v32
	v_ashrrev_i32_e32 v5, 31, v4
	v_ashrrev_i32_e32 v7, 31, v6
	v_lshlrev_b64 v[4:5], 13, v[4:5]
	v_lshlrev_b64 v[6:7], 13, v[6:7]
	v_lshl_add_u64 v[4:5], v[34:35], 0, v[4:5]
	v_lshl_add_u64 v[6:7], v[34:35], 0, v[6:7]
	global_load_dword v4, v[4:5], off nt
	v_or_b32_e32 v8, 14, v32
	global_load_dword v5, v[6:7], off nt
	v_or_b32_e32 v6, 12, v32
	v_ashrrev_i32_e32 v7, 31, v6
	v_ashrrev_i32_e32 v9, 31, v8
	v_lshlrev_b64 v[6:7], 13, v[6:7]
	v_lshlrev_b64 v[8:9], 13, v[8:9]
	v_lshl_add_u64 v[6:7], v[34:35], 0, v[6:7]
	v_lshl_add_u64 v[8:9], v[34:35], 0, v[8:9]
	global_load_dword v6, v[6:7], off nt
	v_or_b32_e32 v10, 18, v32
	global_load_dword v7, v[8:9], off nt
	v_or_b32_e32 v8, 16, v32
	v_ashrrev_i32_e32 v9, 31, v8
	v_ashrrev_i32_e32 v11, 31, v10
	v_lshlrev_b64 v[8:9], 13, v[8:9]
	v_lshlrev_b64 v[10:11], 13, v[10:11]
	v_lshl_add_u64 v[8:9], v[34:35], 0, v[8:9]
	v_lshl_add_u64 v[10:11], v[34:35], 0, v[10:11]
	global_load_dword v8, v[8:9], off nt
	v_or_b32_e32 v12, 22, v32
	global_load_dword v9, v[10:11], off nt
	v_or_b32_e32 v10, 20, v32
	v_ashrrev_i32_e32 v11, 31, v10
	v_ashrrev_i32_e32 v13, 31, v12
	v_lshlrev_b64 v[10:11], 13, v[10:11]
	v_lshlrev_b64 v[12:13], 13, v[12:13]
	v_lshl_add_u64 v[10:11], v[34:35], 0, v[10:11]
	v_lshl_add_u64 v[12:13], v[34:35], 0, v[12:13]
	global_load_dword v10, v[10:11], off nt
	v_or_b32_e32 v14, 26, v32
	global_load_dword v11, v[12:13], off nt
	v_or_b32_e32 v12, 24, v32
	v_ashrrev_i32_e32 v13, 31, v12
	v_ashrrev_i32_e32 v15, 31, v14
	v_lshlrev_b64 v[12:13], 13, v[12:13]
	v_lshlrev_b64 v[14:15], 13, v[14:15]
	v_lshl_add_u64 v[12:13], v[34:35], 0, v[12:13]
	v_lshl_add_u64 v[14:15], v[34:35], 0, v[14:15]
	global_load_dword v12, v[12:13], off nt
	v_or_b32_e32 v16, 30, v32
	global_load_dword v13, v[14:15], off nt
	v_or_b32_e32 v14, 28, v32
	v_ashrrev_i32_e32 v15, 31, v14
	v_ashrrev_i32_e32 v17, 31, v16
	v_lshlrev_b64 v[14:15], 13, v[14:15]
	v_lshlrev_b64 v[16:17], 13, v[16:17]
	v_lshl_add_u64 v[14:15], v[34:35], 0, v[14:15]
	v_lshl_add_u64 v[16:17], v[34:35], 0, v[16:17]
	global_load_dword v14, v[14:15], off nt
	v_or_b32_e32 v18, 34, v32
	global_load_dword v15, v[16:17], off nt
	v_or_b32_e32 v16, 32, v32
; __device__ __forceinline__ void tr_load(const float* W, int N, int item, int lane, float (&wv)[32]) {
;     const int nblk = N / 32, kb = item / nblk, nb = item % nblk, k0 = 64 * kb, n0 = 32 * nb;
; #pragma unroll
;     for (int i = 0; i < 32; ++i) { const int kk = 2 * i + (lane >> 5); wv[i] = __builtin_nontemporal_load(W + (size_t)(k0 + kk) * N + n0 + (lane & 31)); }
; template <int MAP, bool HASG = false, bool PERMW = false>
; __device__ __forceinline__ void transpose_mat(const float* W, int K, int N, bf16_t* WT, LAS float* scr, int gw, int ngw, int lane, const float* gk = nullptr) {
;     ...
;     float wv[32];
;     tr_load(W, N, it, lane, wv);
;     for (;;) {
;         __builtin_amdgcn_sched_barrier(0);
; #pragma unroll
;         for (int i = 0; i < 32; ++i) { const int kk = 2 * i + (lane >> 5); scr[kk * 33 + (lane & 31)] = wv[i]; }
	v_ashrrev_i32_e32 v17, 31, v16
	v_ashrrev_i32_e32 v19, 31, v18
	v_lshlrev_b64 v[16:17], 13, v[16:17]
	v_lshlrev_b64 v[18:19], 13, v[18:19]
	v_lshl_add_u64 v[16:17], v[34:35], 0, v[16:17]
	v_lshl_add_u64 v[18:19], v[34:35], 0, v[18:19]
	global_load_dword v16, v[16:17], off nt
	v_or_b32_e32 v20, 38, v32
	global_load_dword v17, v[18:19], off nt
	v_or_b32_e32 v18, 36, v32
	v_ashrrev_i32_e32 v19, 31, v18
	v_ashrrev_i32_e32 v21, 31, v20
	v_lshlrev_b64 v[18:19], 13, v[18:19]
	v_lshlrev_b64 v[20:21], 13, v[20:21]
	v_lshl_add_u64 v[18:19], v[34:35], 0, v[18:19]
	v_lshl_add_u64 v[20:21], v[34:35], 0, v[20:21]
	global_load_dword v18, v[18:19], off nt
	v_or_b32_e32 v22, 42, v32
	global_load_dword v19, v[20:21], off nt
	v_or_b32_e32 v20, 40, v32
	v_ashrrev_i32_e32 v21, 31, v20
	v_ashrrev_i32_e32 v23, 31, v22
	v_lshlrev_b64 v[20:21], 13, v[20:21]
	v_lshlrev_b64 v[22:23], 13, v[22:23]
	v_lshl_add_u64 v[20:21], v[34:35], 0, v[20:21]
	v_lshl_add_u64 v[22:23], v[34:35], 0, v[22:23]
	global_load_dword v20, v[20:21], off nt
	v_or_b32_e32 v24, 46, v32
	global_load_dword v21, v[22:23], off nt
	v_or_b32_e32 v22, 44, v32
	v_ashrrev_i32_e32 v23, 31, v22
	v_ashrrev_i32_e32 v25, 31, v24
	v_lshlrev_b64 v[22:23], 13, v[22:23]
	v_lshlrev_b64 v[24:25], 13, v[24:25]
	v_lshl_add_u64 v[22:23], v[34:35], 0, v[22:23]
	v_lshl_add_u64 v[24:25], v[34:35], 0, v[24:25]
	global_load_dword v22, v[22:23], off nt
	v_or_b32_e32 v26, 50, v32
	global_load_dword v23, v[24:25], off nt
	v_or_b32_e32 v24, 48, v32
	v_ashrrev_i32_e32 v25, 31, v24
	v_ashrrev_i32_e32 v27, 31, v26
	v_lshlrev_b64 v[24:25], 13, v[24:25]
	v_lshlrev_b64 v[26:27], 13, v[26:27]
	v_lshl_add_u64 v[24:25], v[34:35], 0, v[24:25]
	v_lshl_add_u64 v[26:27], v[34:35], 0, v[26:27]
	global_load_dword v24, v[24:25], off nt
	v_or_b32_e32 v28, 54, v32
	global_load_dword v25, v[26:27], off nt
	v_or_b32_e32 v26, 52, v32
	v_ashrrev_i32_e32 v27, 31, v26
	v_ashrrev_i32_e32 v29, 31, v28
	v_lshlrev_b64 v[26:27], 13, v[26:27]
	v_lshlrev_b64 v[28:29], 13, v[28:29]
	v_lshl_add_u64 v[26:27], v[34:35], 0, v[26:27]
	v_lshl_add_u64 v[28:29], v[34:35], 0, v[28:29]
	global_load_dword v26, v[26:27], off nt
	v_or_b32_e32 v30, 58, v32
	global_load_dword v27, v[28:29], off nt
	v_or_b32_e32 v28, 56, v32
	v_ashrrev_i32_e32 v29, 31, v28
	v_ashrrev_i32_e32 v31, 31, v30
	v_lshlrev_b64 v[28:29], 13, v[28:29]
	v_lshlrev_b64 v[30:31], 13, v[30:31]
	v_lshl_add_u64 v[28:29], v[34:35], 0, v[28:29]
	v_lshl_add_u64 v[30:31], v[34:35], 0, v[30:31]
	global_load_dword v28, v[28:29], off nt
	v_lshlrev_b32_e32 v36, 4, v132
	global_load_dword v29, v[30:31], off nt
	v_or_b32_e32 v30, 60, v32
	v_or_b32_e32 v32, 62, v32
	v_ashrrev_i32_e32 v31, 31, v30
	v_ashrrev_i32_e32 v33, 31, v32
	v_lshlrev_b64 v[30:31], 13, v[30:31]
	v_lshlrev_b64 v[32:33], 13, v[32:33]
	v_lshl_add_u64 v[30:31], v[34:35], 0, v[30:31]
	v_lshl_add_u64 v[32:33], v[34:35], 0, v[32:33]
	global_load_dword v30, v[30:31], off nt
	v_lshlrev_b32_e32 v35, 3, v132
	global_load_dword v31, v[32:33], off nt
	v_and_b32_e32 v35, 56, v35
	v_add_u32_e32 v34, s26, v48
	v_mul_u32_u24_e32 v35, 0x84, v35
	v_lshl_add_u64 v[32:33], s[14:15], 0, v[48:49]
	v_and_b32_e32 v38, 48, v36
	v_add3_u32 v39, s26, v35, v139
	v_lshl_or_b32 v40, s6, 11, v140
	s_lshl_b32 s18, s8, 11
	s_lshl_b32 s20, s6, 5
	s_lshl_b32 s19, s8, 5
	v_add_u32_e32 v41, v34, v136
	s_mov_b32 s28, s6
	v_readlane_b32 s57, v254, 61
	v_readlane_b32 s58, v254, 62
	v_readlane_b32 s59, v254, 63
	v_readlane_b32 s60, v255, 0
	v_readlane_b32 s61, v255, 1
	v_readlane_b32 s62, v255, 2
	v_readlane_b32 s63, v255, 3
	v_readlane_b32 s66, v255, 6
	v_readlane_b32 s67, v255, 7
	v_readlane_b32 s68, v255, 8
	v_readlane_b32 s69, v255, 9
	v_readlane_b32 s70, v255, 10
	v_readlane_b32 s71, v255, 11
	s_branch .LBB0_39

; #define LAS __attribute__((address_space(3)))
; __device__ __forceinline__ void tr_load(const float* W, int N, int item, int lane, float (&wv)[32]) {
;     const int nblk = N / 32, kb = item / nblk, nb = item % nblk, k0 = 64 * kb, n0 = 32 * nb;
; #pragma unroll
;     for (int i = 0; i < 32; ++i) { const int kk = 2 * i + (lane >> 5); wv[i] = __builtin_nontemporal_load(W + (size_t)(k0 + kk) * N + n0 + (lane & 31)); }
; template <int MAP, bool HASG = false, bool PERMW = false>
; __device__ __forceinline__ void transpose_mat(const float* W, int K, int N, bf16_t* WT, LAS float* scr, int gw, int ngw, int lane, const float* gk = nullptr) {
;     const int nitems = (K / 64) * (N / 32);
;     int it = gw;
;     if (it >= nitems) return;
;     float wv[32];
;     tr_load(W, N, it, lane, wv);
.LBB0_83:
	s_andn2_b64 vcc, exec, s[10:11]
	s_branch .LBB0_90
	s_add_u32 s10, s7, 0xb600000
	v_readlane_b32 s56, v254, 0
	s_addc_u32 s11, s25, 0
	s_lshl_b64 s[0:1], s[90:91], 2
	v_readlane_b32 s66, v254, 10
	v_readlane_b32 s67, v254, 11
	s_add_u32 s0, s66, s0
	s_addc_u32 s1, s67, s1
	s_ashr_i32 s4, s6, 31
	s_lshr_b32 s4, s4, 26
	s_add_i32 s4, s6, s4
	s_and_b32 s5, s4, 0xffffffc0
	s_sub_i32 s4, s6, s5
	s_lshl_b32 s4, s4, 5
	v_or_b32_e32 v32, s5, v134
	s_ashr_i32 s5, s4, 31
	s_lshl_b64 s[4:5], s[4:5], 2
	s_add_u32 s4, s0, s4
	s_waitcnt vmcnt(0)
	v_or_b32_e32 v2, 2, v32
	s_addc_u32 s5, s1, s5
	v_mov_b32_e32 v49, v193
	v_ashrrev_i32_e32 v33, 31, v32
	s_waitcnt vmcnt(32)
	v_ashrrev_i32_e32 v3, 31, v2
	v_lshl_add_u64 v[34:35], s[4:5], 0, v[48:49]
	v_lshlrev_b64 v[0:1], 13, v[32:33]
	v_lshlrev_b64 v[2:3], 13, v[2:3]
	v_lshl_add_u64 v[0:1], v[34:35], 0, v[0:1]
	v_lshl_add_u64 v[2:3], v[34:35], 0, v[2:3]
	global_load_dword v0, v[0:1], off nt
	s_waitcnt vmcnt(32)
	v_or_b32_e32 v4, 6, v32
	global_load_dword v1, v[2:3], off nt
	v_or_b32_e32 v2, 4, v32
	v_ashrrev_i32_e32 v3, 31, v2
	s_waitcnt vmcnt(32)
	v_ashrrev_i32_e32 v5, 31, v4
	v_lshlrev_b64 v[2:3], 13, v[2:3]
	v_lshlrev_b64 v[4:5], 13, v[4:5]
	v_lshl_add_u64 v[2:3], v[34:35], 0, v[2:3]
	v_lshl_add_u64 v[4:5], v[34:35], 0, v[4:5]
	global_load_dword v2, v[2:3], off nt
	s_waitcnt vmcnt(32)
	v_or_b32_e32 v6, 10, v32
	global_load_dword v3, v[4:5], off nt
	v_or_b32_e32 v4, 8, v32
	v_ashrrev_i32_e32 v5, 31, v4
	s_waitcnt vmcnt(32)
	v_ashrrev_i32_e32 v7, 31, v6
	v_lshlrev_b64 v[4:5], 13, v[4:5]
	v_lshlrev_b64 v[6:7], 13, v[6:7]
	v_lshl_add_u64 v[4:5], v[34:35], 0, v[4:5]
	v_lshl_add_u64 v[6:7], v[34:35], 0, v[6:7]
	global_load_dword v4, v[4:5], off nt
	s_waitcnt vmcnt(32)
	v_or_b32_e32 v8, 14, v32
	global_load_dword v5, v[6:7], off nt
	v_or_b32_e32 v6, 12, v32
	v_ashrrev_i32_e32 v7, 31, v6
	s_waitcnt vmcnt(32)
	v_ashrrev_i32_e32 v9, 31, v8
	v_lshlrev_b64 v[6:7], 13, v[6:7]
	v_lshlrev_b64 v[8:9], 13, v[8:9]
	v_lshl_add_u64 v[6:7], v[34:35], 0, v[6:7]
	v_lshl_add_u64 v[8:9], v[34:35], 0, v[8:9]
	global_load_dword v6, v[6:7], off nt
	s_waitcnt vmcnt(32)
	v_or_b32_e32 v10, 18, v32
	global_load_dword v7, v[8:9], off nt
	v_or_b32_e32 v8, 16, v32
	v_ashrrev_i32_e32 v9, 31, v8
	s_waitcnt vmcnt(32)
	v_ashrrev_i32_e32 v11, 31, v10
	v_lshlrev_b64 v[8:9], 13, v[8:9]
	v_lshlrev_b64 v[10:11], 13, v[10:11]
	v_lshl_add_u64 v[8:9], v[34:35], 0, v[8:9]
	v_lshl_add_u64 v[10:11], v[34:35], 0, v[10:11]
	global_load_dword v8, v[8:9], off nt
	s_waitcnt vmcnt(32)
	v_or_b32_e32 v12, 22, v32
	global_load_dword v9, v[10:11], off nt
	v_or_b32_e32 v10, 20, v32
	v_ashrrev_i32_e32 v11, 31, v10
	s_waitcnt vmcnt(32)
	v_ashrrev_i32_e32 v13, 31, v12
	v_lshlrev_b64 v[10:11], 13, v[10:11]
	v_lshlrev_b64 v[12:13], 13, v[12:13]
	v_lshl_add_u64 v[10:11], v[34:35], 0, v[10:11]
	v_lshl_add_u64 v[12:13], v[34:35], 0, v[12:13]
	global_load_dword v10, v[10:11], off nt
	s_waitcnt vmcnt(32)
	v_or_b32_e32 v14, 26, v32
	global_load_dword v11, v[12:13], off nt
	v_or_b32_e32 v12, 24, v32
	v_ashrrev_i32_e32 v13, 31, v12
	s_waitcnt vmcnt(32)
	v_ashrrev_i32_e32 v15, 31, v14
	v_lshlrev_b64 v[12:13], 13, v[12:13]
	v_lshlrev_b64 v[14:15], 13, v[14:15]
	v_lshl_add_u64 v[12:13], v[34:35], 0, v[12:13]
	v_lshl_add_u64 v[14:15], v[34:35], 0, v[14:15]
	global_load_dword v12, v[12:13], off nt
	s_waitcnt vmcnt(32)
	v_or_b32_e32 v16, 30, v32
	global_load_dword v13, v[14:15], off nt
	v_or_b32_e32 v14, 28, v32
	v_ashrrev_i32_e32 v15, 31, v14
	s_waitcnt vmcnt(32)
	v_ashrrev_i32_e32 v17, 31, v16
	v_lshlrev_b64 v[14:15], 13, v[14:15]
	v_lshlrev_b64 v[16:17], 13, v[16:17]
	v_lshl_add_u64 v[14:15], v[34:35], 0, v[14:15]
	v_lshl_add_u64 v[16:17], v[34:35], 0, v[16:17]
	global_load_dword v14, v[14:15], off nt
	s_waitcnt vmcnt(32)
	v_or_b32_e32 v18, 34, v32
	global_load_dword v15, v[16:17], off nt
	v_or_b32_e32 v16, 32, v32
	v_ashrrev_i32_e32 v17, 31, v16
	s_waitcnt vmcnt(32)
; __device__ __forceinline__ void tr_load(const float* W, int N, int item, int lane, float (&wv)[32]) {
;     const int nblk = N / 32, kb = item / nblk, nb = item % nblk, k0 = 64 * kb, n0 = 32 * nb;
; #pragma unroll
;     for (int i = 0; i < 32; ++i) { const int kk = 2 * i + (lane >> 5); wv[i] = __builtin_nontemporal_load(W + (size_t)(k0 + kk) * N + n0 + (lane & 31)); }
; template <int MAP, bool HASG = false, bool PERMW = false>
; __device__ __forceinline__ void transpose_mat(const float* W, int K, int N, bf16_t* WT, LAS float* scr, int gw, int ngw, int lane, const float* gk = nullptr) {
;     ...
;     float wv[32];
;     tr_load(W, N, it, lane, wv);
;     for (;;) {
;         __builtin_amdgcn_sched_barrier(0);
; #pragma unroll
;         for (int i = 0; i < 32; ++i) { const int kk = 2 * i + (lane >> 5); scr[kk * 33 + (lane & 31)] = wv[i]; }
	v_ashrrev_i32_e32 v19, 31, v18
	v_lshlrev_b64 v[16:17], 13, v[16:17]
	v_lshlrev_b64 v[18:19], 13, v[18:19]
	v_lshl_add_u64 v[16:17], v[34:35], 0, v[16:17]
	v_lshl_add_u64 v[18:19], v[34:35], 0, v[18:19]
	global_load_dword v16, v[16:17], off nt
	s_waitcnt vmcnt(32)
	v_or_b32_e32 v20, 38, v32
	global_load_dword v17, v[18:19], off nt
	v_or_b32_e32 v18, 36, v32
	v_ashrrev_i32_e32 v19, 31, v18
	s_waitcnt vmcnt(32)
	v_ashrrev_i32_e32 v21, 31, v20
	v_lshlrev_b64 v[18:19], 13, v[18:19]
	v_lshlrev_b64 v[20:21], 13, v[20:21]
	v_lshl_add_u64 v[18:19], v[34:35], 0, v[18:19]
	v_lshl_add_u64 v[20:21], v[34:35], 0, v[20:21]
	global_load_dword v18, v[18:19], off nt
	s_waitcnt vmcnt(32)
	v_or_b32_e32 v22, 42, v32
	global_load_dword v19, v[20:21], off nt
	v_or_b32_e32 v20, 40, v32
	v_ashrrev_i32_e32 v21, 31, v20
	s_waitcnt vmcnt(32)
	v_ashrrev_i32_e32 v23, 31, v22
	v_lshlrev_b64 v[20:21], 13, v[20:21]
	v_lshlrev_b64 v[22:23], 13, v[22:23]
	v_lshl_add_u64 v[20:21], v[34:35], 0, v[20:21]
	v_lshl_add_u64 v[22:23], v[34:35], 0, v[22:23]
	global_load_dword v20, v[20:21], off nt
	s_waitcnt vmcnt(32)
	v_or_b32_e32 v24, 46, v32
	global_load_dword v21, v[22:23], off nt
	v_or_b32_e32 v22, 44, v32
	v_ashrrev_i32_e32 v23, 31, v22
	s_waitcnt vmcnt(32)
	v_ashrrev_i32_e32 v25, 31, v24
	v_lshlrev_b64 v[22:23], 13, v[22:23]
	v_lshlrev_b64 v[24:25], 13, v[24:25]
	v_lshl_add_u64 v[22:23], v[34:35], 0, v[22:23]
	v_lshl_add_u64 v[24:25], v[34:35], 0, v[24:25]
	global_load_dword v22, v[22:23], off nt
	s_waitcnt vmcnt(32)
	v_or_b32_e32 v26, 50, v32
	global_load_dword v23, v[24:25], off nt
	v_or_b32_e32 v24, 48, v32
	v_ashrrev_i32_e32 v25, 31, v24
	s_waitcnt vmcnt(32)
	v_ashrrev_i32_e32 v27, 31, v26
	v_lshlrev_b64 v[24:25], 13, v[24:25]
	v_lshlrev_b64 v[26:27], 13, v[26:27]
	v_lshl_add_u64 v[24:25], v[34:35], 0, v[24:25]
	v_lshl_add_u64 v[26:27], v[34:35], 0, v[26:27]
	global_load_dword v24, v[24:25], off nt
	s_waitcnt vmcnt(32)
	v_or_b32_e32 v28, 54, v32
	global_load_dword v25, v[26:27], off nt
	v_or_b32_e32 v26, 52, v32
	v_ashrrev_i32_e32 v27, 31, v26
	s_waitcnt vmcnt(32)
	v_ashrrev_i32_e32 v29, 31, v28
	v_lshlrev_b64 v[26:27], 13, v[26:27]
	v_lshlrev_b64 v[28:29], 13, v[28:29]
	v_lshl_add_u64 v[26:27], v[34:35], 0, v[26:27]
	v_lshl_add_u64 v[28:29], v[34:35], 0, v[28:29]
	global_load_dword v26, v[26:27], off nt
	s_waitcnt vmcnt(32)
	v_or_b32_e32 v30, 58, v32
	global_load_dword v27, v[28:29], off nt
	v_or_b32_e32 v28, 56, v32
	v_ashrrev_i32_e32 v29, 31, v28
	s_waitcnt vmcnt(32)
	v_ashrrev_i32_e32 v31, 31, v30
	v_lshlrev_b64 v[28:29], 13, v[28:29]
	v_lshlrev_b64 v[30:31], 13, v[30:31]
	v_lshl_add_u64 v[28:29], v[34:35], 0, v[28:29]
	v_lshl_add_u64 v[30:31], v[34:35], 0, v[30:31]
	global_load_dword v28, v[28:29], off nt
	v_lshlrev_b32_e32 v36, 4, v132
	global_load_dword v29, v[30:31], off nt
	v_or_b32_e32 v30, 60, v32
	v_or_b32_e32 v32, 62, v32
	v_ashrrev_i32_e32 v31, 31, v30
	v_ashrrev_i32_e32 v33, 31, v32
	v_lshlrev_b64 v[30:31], 13, v[30:31]
	v_lshlrev_b64 v[32:33], 13, v[32:33]
	v_lshl_add_u64 v[30:31], v[34:35], 0, v[30:31]
	v_lshl_add_u64 v[32:33], v[34:35], 0, v[32:33]
	global_load_dword v30, v[30:31], off nt
	v_lshlrev_b32_e32 v35, 3, v132
	global_load_dword v31, v[32:33], off nt
	v_and_b32_e32 v35, 56, v35
	v_add_u32_e32 v34, s26, v48
	v_mul_u32_u24_e32 v35, 0x84, v35
	v_lshl_add_u64 v[32:33], s[0:1], 0, v[48:49]
	v_and_b32_e32 v38, 48, v36
	v_add3_u32 v39, s26, v35, v139
	v_lshl_or_b32 v40, s6, 11, v140
	s_lshl_b32 s12, s8, 11
	s_lshl_b32 s14, s6, 5
	s_lshl_b32 s13, s8, 5
	v_add_u32_e32 v41, v34, v136
	s_mov_b32 s16, s6
	v_readlane_b32 s57, v254, 1
	v_readlane_b32 s58, v254, 2
	v_readlane_b32 s59, v254, 3
	v_readlane_b32 s60, v254, 4
	v_readlane_b32 s61, v254, 5
	v_readlane_b32 s62, v254, 6
	v_readlane_b32 s63, v254, 7
	v_readlane_b32 s64, v254, 8
	v_readlane_b32 s65, v254, 9
	v_readlane_b32 s68, v254, 12
	v_readlane_b32 s69, v254, 13
	v_readlane_b32 s70, v254, 14
	v_readlane_b32 s71, v254, 15
	s_branch .LBB0_86

; #define LAS __attribute__((address_space(3)))
; __device__ __forceinline__ unsigned pk2(float lo, float hi) { f32x2 f = {lo, hi}; bf16x2_t b = __builtin_convertvector(f, bf16x2_t); return __builtin_bit_cast(unsigned, b); }
; template <int MAP, bool HASG, bool PERMW>
; __device__ __forceinline__ void tr_store(int K, int N, bf16_t* WT, LAS float* scr, int item, int lane, const float* gk) {
;     const int nblk = N / 32, kb = item / nblk, nb = item % nblk, k0 = 64 * kb, n0 = 32 * nb;
;     asm volatile("s_waitcnt lgkmcnt(0)" ::: "memory");
;     const int c = lane & 7;
;     f32x4 g0 = {1.f, 1.f, 1.f, 1.f}, g1 = {1.f, 1.f, 1.f, 1.f};
;     if (HASG) { g0 = *(const f32x4*)(gk + k0 + 8 * c); g1 = *(const f32x4*)(gk + k0 + 8 * c + 4); }
; #pragma unroll
;     for (int j = 0; j < 4; ++j) { const int n = (lane >> 3) + 8 * j; const LAS float* s = scr + (8 * c) * 33 + n;
;         u32x4 o; o.x = pk2(s[0 * 33] * g0[0], s[1 * 33] * g0[1]); o.y = pk2(s[2 * 33] * g0[2], s[3 * 33] * g0[3]); o.z = pk2(s[4 * 33] * g1[0], s[5 * 33] * g1[1]); o.w = pk2(s[6 * 33] * g1[2], s[7 * 33] * g1[3]);
;         const int wr_ = rowmap<MAP>(n0 + n), slot_ = PERMW ? ((wr_ & ~31) + invperm32(wr_ & 31)) : wr_;
;         *(u32x4*)((char*)WT + tiled_off(slot_, k0 + 8 * c, K / 64)) = o; }
; template <int MAP, bool HASG = false, bool PERMW = false>
; __device__ __forceinline__ void transpose_mat(const float* W, int K, int N, bf16_t* WT, LAS float* scr, int gw, int ngw, int lane, const float* gk = nullptr) {
;     const int nitems = (K / 64) * (N / 32);
;     int it = gw;
;     if (it >= nitems) return;
;     float wv[32];
;     tr_load(W, N, it, lane, wv);
.LBB0_158:
	s_cmpk_lt_u32 s2, 0x80
	s_cbranch_scc1 .Ltc1_done
	v_writelane_b32 v255, s4, 24
	v_writelane_b32 v255, s5, 25
	v_writelane_b32 v255, s6, 26
	v_writelane_b32 v255, s7, 27
	v_writelane_b32 v255, s8, 28
	v_writelane_b32 v255, s9, 29
	v_writelane_b32 v255, s10, 30
	v_writelane_b32 v255, s11, 31
	v_writelane_b32 v255, s12, 32
	v_writelane_b32 v255, s13, 33
	v_writelane_b32 v255, s14, 34
	v_writelane_b32 v255, s15, 35
	v_writelane_b32 v255, s16, 36
	v_writelane_b32 v255, s17, 37
	v_writelane_b32 v255, s18, 38
	v_writelane_b32 v255, s19, 39
	v_readlane_b32 s4, v255, 4
	v_readlane_b32 s5, v255, 5
	v_readfirstlane_b32 s8, v234
	s_nop 3
	s_and_b32 s6, s60, 0x2c00000
	s_add_u32 s4, s4, s6
	s_addc_u32 s5, s5, 0
	s_add_u32 s6, s76, 0x2c00000
	s_addc_u32 s7, s77, 0
	s_lshr_b32 s8, s8, 6
	s_sub_u32 s9, s2, 0x80
	s_lshl_b32 s9, s9, 3
	s_add_u32 s9, s9, s8
	s_mul_i32 s10, s8, 0x2100
	v_and_b32_e32 v0, 63, v234
	v_and_b32_e32 v1, 31, v0
	v_lshrrev_b32_e32 v2, 5, v0
	v_lshlrev_b32_e32 v3, 13, v2
	v_lshl_add_u32 v3, v1, 2, v3
	v_mul_u32_u24_e32 v4, 33, v2
	v_add_u32_e32 v4, v4, v1
	v_lshl_add_u32 v4, v4, 2, s10
	v_and_b32_e32 v5, 7, v0
	v_lshrrev_b32_e32 v6, 3, v0
	v_mul_u32_u24_e32 v7, 0x108, v5
	v_add_u32_e32 v7, v7, v6
	v_lshl_add_u32 v7, v7, 2, s10
	v_lshrrev_b32_e32 v8, 2, v5
	v_lshlrev_b32_e32 v8, 10, v8
	v_and_b32_e32 v9, 3, v5
	v_lshlrev_b32_e32 v9, 4, v9
	v_lshl_add_u32 v8, v6, 6, v8
	v_add_u32_e32 v8, v8, v9
	v_xor_b32_e32 v9, 32, v8
	v_add_u32_e32 v9, 0x200, v9
; #define LAS __attribute__((address_space(3)))
; __device__ __forceinline__ unsigned pk2(float lo, float hi) { f32x2 f = {lo, hi}; bf16x2_t b = __builtin_convertvector(f, bf16x2_t); return __builtin_bit_cast(unsigned, b); }
; __device__ __forceinline__ void tr_load(const float* W, int N, int item, int lane, float (&wv)[32]) {
;     const int nblk = N / 32, kb = item / nblk, nb = item % nblk, k0 = 64 * kb, n0 = 32 * nb;
; #pragma unroll
;     for (int i = 0; i < 32; ++i) { const int kk = 2 * i + (lane >> 5); wv[i] = __builtin_nontemporal_load(W + (size_t)(k0 + kk) * N + n0 + (lane & 31)); }
; }
; template <int MAP, bool HASG, bool PERMW>
; __device__ __forceinline__ void tr_store(int K, int N, bf16_t* WT, LAS float* scr, int item, int lane, const float* gk) {
;     const int nblk = N / 32, kb = item / nblk, nb = item % nblk, k0 = 64 * kb, n0 = 32 * nb;
;     asm volatile("s_waitcnt lgkmcnt(0)" ::: "memory");
;     const int c = lane & 7;
;     f32x4 g0 = {1.f, 1.f, 1.f, 1.f}, g1 = {1.f, 1.f, 1.f, 1.f};
;     if (HASG) { g0 = *(const f32x4*)(gk + k0 + 8 * c); g1 = *(const f32x4*)(gk + k0 + 8 * c + 4); }
; #pragma unroll
;     for (int j = 0; j < 4; ++j) { const int n = (lane >> 3) + 8 * j; const LAS float* s = scr + (8 * c) * 33 + n;
;         u32x4 o; o.x = pk2(s[0 * 33] * g0[0], s[1 * 33] * g0[1]); o.y = pk2(s[2 * 33] * g0[2], s[3 * 33] * g0[3]); o.z = pk2(s[4 * 33] * g1[0], s[5 * 33] * g1[1]); o.w = pk2(s[6 * 33] * g1[2], s[7 * 33] * g1[3]);
;         const int wr_ = rowmap<MAP>(n0 + n), slot_ = PERMW ? ((wr_ & ~31) + invperm32(wr_ & 31)) : wr_;
;         *(u32x4*)((char*)WT + tiled_off(slot_, k0 + 8 * c, K / 64)) = o; }
; template <int MAP, bool HASG = false, bool PERMW = false>
; __device__ __forceinline__ void transpose_mat(const float* W, int K, int N, bf16_t* WT, LAS float* scr, int gw, int ngw, int lane, const float* gk = nullptr) {
;     ...
;     for (;;) {
;         __builtin_amdgcn_sched_barrier(0);
; #pragma unroll
;         for (int i = 0; i < 32; ++i) { const int kk = 2 * i + (lane >> 5); scr[kk * 33 + (lane & 31)] = wv[i]; }
;         __builtin_amdgcn_sched_barrier(0);
;         const int nx = it + ngw;
;         if (nx < nitems) tr_load(W, N, nx, lane, wv);
;         __builtin_amdgcn_sched_barrier(0);
;         tr_store<MAP, HASG, PERMW>(K, N, WT, scr, it, lane, gk);
;         if (nx >= nitems) break;
;         it = nx;
;     }
.Ltc1_loop:
	s_cmpk_ge_u32 s9, 0x1600
	s_cbranch_scc1 .Ltc1_exit
	s_lshr_b32 s11, s9, 6
	s_and_b32 s12, s9, 63
	s_lshl_b32 s13, s11, 19
	s_lshl_b32 s14, s12, 7
	s_add_u32 s13, s13, s14
	s_add_u32 s14, s4, s13
	s_addc_u32 s15, s5, 0
	global_load_dword v16, v3, s[14:15] nt
	s_add_u32 s14, s14, 0x4000
	s_addc_u32 s15, s15, 0
	global_load_dword v17, v3, s[14:15] nt
	s_add_u32 s14, s14, 0x4000
	s_addc_u32 s15, s15, 0
	global_load_dword v18, v3, s[14:15] nt
	s_add_u32 s14, s14, 0x4000
	s_addc_u32 s15, s15, 0
	global_load_dword v19, v3, s[14:15] nt
	s_add_u32 s14, s14, 0x4000
	s_addc_u32 s15, s15, 0
	global_load_dword v20, v3, s[14:15] nt
	s_add_u32 s14, s14, 0x4000
	s_addc_u32 s15, s15, 0
	global_load_dword v21, v3, s[14:15] nt
	s_add_u32 s14, s14, 0x4000
	s_addc_u32 s15, s15, 0
	global_load_dword v22, v3, s[14:15] nt
	s_add_u32 s14, s14, 0x4000
	s_addc_u32 s15, s15, 0
	global_load_dword v23, v3, s[14:15] nt
	s_add_u32 s14, s14, 0x4000
	s_addc_u32 s15, s15, 0
	global_load_dword v24, v3, s[14:15] nt
	s_add_u32 s14, s14, 0x4000
	s_addc_u32 s15, s15, 0
	global_load_dword v25, v3, s[14:15] nt
	s_add_u32 s14, s14, 0x4000
	s_addc_u32 s15, s15, 0
	global_load_dword v26, v3, s[14:15] nt
	s_add_u32 s14, s14, 0x4000
	s_addc_u32 s15, s15, 0
	global_load_dword v27, v3, s[14:15] nt
	s_add_u32 s14, s14, 0x4000
	s_addc_u32 s15, s15, 0
	global_load_dword v28, v3, s[14:15] nt
	s_add_u32 s14, s14, 0x4000
	s_addc_u32 s15, s15, 0
	global_load_dword v29, v3, s[14:15] nt
	s_add_u32 s14, s14, 0x4000
	s_addc_u32 s15, s15, 0
	global_load_dword v30, v3, s[14:15] nt
	s_add_u32 s14, s14, 0x4000
	s_addc_u32 s15, s15, 0
	global_load_dword v31, v3, s[14:15] nt
	s_add_u32 s14, s14, 0x4000
	s_addc_u32 s15, s15, 0
	global_load_dword v32, v3, s[14:15] nt
	s_add_u32 s14, s14, 0x4000
	s_addc_u32 s15, s15, 0
	global_load_dword v33, v3, s[14:15] nt
	s_add_u32 s14, s14, 0x4000
	s_addc_u32 s15, s15, 0
	global_load_dword v34, v3, s[14:15] nt
	s_add_u32 s14, s14, 0x4000
	s_addc_u32 s15, s15, 0
	global_load_dword v35, v3, s[14:15] nt
	s_add_u32 s14, s14, 0x4000
	s_addc_u32 s15, s15, 0
	global_load_dword v36, v3, s[14:15] nt
	s_add_u32 s14, s14, 0x4000
	s_addc_u32 s15, s15, 0
	global_load_dword v37, v3, s[14:15] nt
	s_add_u32 s14, s14, 0x4000
	s_addc_u32 s15, s15, 0
	global_load_dword v38, v3, s[14:15] nt
	s_add_u32 s14, s14, 0x4000
	s_addc_u32 s15, s15, 0
	global_load_dword v39, v3, s[14:15] nt
	s_add_u32 s14, s14, 0x4000
	s_addc_u32 s15, s15, 0
	global_load_dword v40, v3, s[14:15] nt
	s_add_u32 s14, s14, 0x4000
	s_addc_u32 s15, s15, 0
	global_load_dword v41, v3, s[14:15] nt
	s_add_u32 s14, s14, 0x4000
	s_addc_u32 s15, s15, 0
	global_load_dword v42, v3, s[14:15] nt
	s_add_u32 s14, s14, 0x4000
	s_addc_u32 s15, s15, 0
	global_load_dword v43, v3, s[14:15] nt
	s_add_u32 s14, s14, 0x4000
	s_addc_u32 s15, s15, 0
	global_load_dword v44, v3, s[14:15] nt
	s_add_u32 s14, s14, 0x4000
	s_addc_u32 s15, s15, 0
	global_load_dword v45, v3, s[14:15] nt
	s_add_u32 s14, s14, 0x4000
	s_addc_u32 s15, s15, 0
	global_load_dword v46, v3, s[14:15] nt
	s_add_u32 s14, s14, 0x4000
	s_addc_u32 s15, s15, 0
	global_load_dword v47, v3, s[14:15] nt
	s_lshr_b32 s16, s12, 2
	s_mul_i32 s16, s16, 0x58
	s_add_u32 s16, s16, s11
	s_lshl_b32 s16, s16, 14
	s_and_b32 s17, s12, 3
	s_lshl_b32 s17, s17, 12
	s_add_u32 s16, s16, s17
	s_add_u32 s16, s6, s16
	s_addc_u32 s17, s7, 0
	s_waitcnt vmcnt(0)
	ds_write_b32 v4, v16
	ds_write_b32 v4, v17 offset:264
	ds_write_b32 v4, v18 offset:528
	ds_write_b32 v4, v19 offset:792
	ds_write_b32 v4, v20 offset:1056
	ds_write_b32 v4, v21 offset:1320
	ds_write_b32 v4, v22 offset:1584
	ds_write_b32 v4, v23 offset:1848
	ds_write_b32 v4, v24 offset:2112
	ds_write_b32 v4, v25 offset:2376
	ds_write_b32 v4, v26 offset:2640
	ds_write_b32 v4, v27 offset:2904
	ds_write_b32 v4, v28 offset:3168
	ds_write_b32 v4, v29 offset:3432
	ds_write_b32 v4, v30 offset:3696
	ds_write_b32 v4, v31 offset:3960
	ds_write_b32 v4, v32 offset:4224
	ds_write_b32 v4, v33 offset:4488
	ds_write_b32 v4, v34 offset:4752
	ds_write_b32 v4, v35 offset:5016
	ds_write_b32 v4, v36 offset:5280
	ds_write_b32 v4, v37 offset:5544
	ds_write_b32 v4, v38 offset:5808
	ds_write_b32 v4, v39 offset:6072
	ds_write_b32 v4, v40 offset:6336
	ds_write_b32 v4, v41 offset:6600
	ds_write_b32 v4, v42 offset:6864
	ds_write_b32 v4, v43 offset:7128
	ds_write_b32 v4, v44 offset:7392
	ds_write_b32 v4, v45 offset:7656
	ds_write_b32 v4, v46 offset:7920
	ds_write_b32 v4, v47 offset:8184
	s_waitcnt lgkmcnt(0)
	ds_read_b32 v48, v7
	ds_read_b32 v49, v7 offset:132
	ds_read_b32 v50, v7 offset:264
	ds_read_b32 v51, v7 offset:396
	ds_read_b32 v52, v7 offset:528
	ds_read_b32 v53, v7 offset:660
	ds_read_b32 v54, v7 offset:792
	ds_read_b32 v55, v7 offset:924
	ds_read_b32 v56, v7 offset:32
	ds_read_b32 v57, v7 offset:164
	ds_read_b32 v58, v7 offset:296
	ds_read_b32 v59, v7 offset:428
	ds_read_b32 v60, v7 offset:560
	ds_read_b32 v61, v7 offset:692
	ds_read_b32 v62, v7 offset:824
	ds_read_b32 v63, v7 offset:956
	ds_read_b32 v64, v7 offset:64
	ds_read_b32 v65, v7 offset:196
	ds_read_b32 v66, v7 offset:328
	ds_read_b32 v67, v7 offset:460
	ds_read_b32 v68, v7 offset:592
	ds_read_b32 v69, v7 offset:724
	ds_read_b32 v70, v7 offset:856
	ds_read_b32 v71, v7 offset:988
	ds_read_b32 v72, v7 offset:96
	ds_read_b32 v73, v7 offset:228
	ds_read_b32 v74, v7 offset:360
	ds_read_b32 v75, v7 offset:492
	ds_read_b32 v76, v7 offset:624
	ds_read_b32 v77, v7 offset:756
	ds_read_b32 v78, v7 offset:888
	ds_read_b32 v79, v7 offset:1020
	s_waitcnt lgkmcnt(0)
	v_cvt_pk_bf16_f32 v48, v48, v49
	v_cvt_pk_bf16_f32 v49, v50, v51
	v_cvt_pk_bf16_f32 v50, v52, v53
	v_cvt_pk_bf16_f32 v51, v54, v55
	global_store_dwordx4 v8, v[48:51], s[16:17]
	v_cvt_pk_bf16_f32 v56, v56, v57
	v_cvt_pk_bf16_f32 v57, v58, v59
	v_cvt_pk_bf16_f32 v58, v60, v61
	v_cvt_pk_bf16_f32 v59, v62, v63
	global_store_dwordx4 v9, v[56:59], s[16:17]
	v_cvt_pk_bf16_f32 v64, v64, v65
	v_cvt_pk_bf16_f32 v65, v66, v67
	v_cvt_pk_bf16_f32 v66, v68, v69
	v_cvt_pk_bf16_f32 v67, v70, v71
	global_store_dwordx4 v8, v[64:67], s[16:17] offset:2048
	v_cvt_pk_bf16_f32 v72, v72, v73
	v_cvt_pk_bf16_f32 v73, v74, v75
	v_cvt_pk_bf16_f32 v74, v76, v77
	v_cvt_pk_bf16_f32 v75, v78, v79
	global_store_dwordx4 v9, v[72:75], s[16:17] offset:2048
	s_add_u32 s9, s9, 0x400
	s_branch .Ltc1_loop
.Ltc1_exit:
	v_readlane_b32 s4, v255, 24
	v_readlane_b32 s5, v255, 25
	v_readlane_b32 s6, v255, 26
	v_readlane_b32 s7, v255, 27
	v_readlane_b32 s8, v255, 28
	v_readlane_b32 s9, v255, 29
	v_readlane_b32 s10, v255, 30
	v_readlane_b32 s11, v255, 31
	v_readlane_b32 s12, v255, 32
	v_readlane_b32 s13, v255, 33
	v_readlane_b32 s14, v255, 34
	v_readlane_b32 s15, v255, 35
	v_readlane_b32 s16, v255, 36
	v_readlane_b32 s17, v255, 37
	v_readlane_b32 s18, v255, 38
	v_readlane_b32 s19, v255, 39
	s_nop 3

; #define LAS __attribute__((address_space(3)))
; __device__ __forceinline__ unsigned pk2(float lo, float hi) { f32x2 f = {lo, hi}; bf16x2_t b = __builtin_convertvector(f, bf16x2_t); return __builtin_bit_cast(unsigned, b); }
; template <int MAP, bool HASG, bool PERMW>
; __device__ __forceinline__ void tr_store(int K, int N, bf16_t* WT, LAS float* scr, int item, int lane, const float* gk) {
;     const int nblk = N / 32, kb = item / nblk, nb = item % nblk, k0 = 64 * kb, n0 = 32 * nb;
;     asm volatile("s_waitcnt lgkmcnt(0)" ::: "memory");
;     const int c = lane & 7;
;     f32x4 g0 = {1.f, 1.f, 1.f, 1.f}, g1 = {1.f, 1.f, 1.f, 1.f};
;     if (HASG) { g0 = *(const f32x4*)(gk + k0 + 8 * c); g1 = *(const f32x4*)(gk + k0 + 8 * c + 4); }
; #pragma unroll
;     for (int j = 0; j < 4; ++j) { const int n = (lane >> 3) + 8 * j; const LAS float* s = scr + (8 * c) * 33 + n;
;         u32x4 o; o.x = pk2(s[0 * 33] * g0[0], s[1 * 33] * g0[1]); o.y = pk2(s[2 * 33] * g0[2], s[3 * 33] * g0[3]); o.z = pk2(s[4 * 33] * g1[0], s[5 * 33] * g1[1]); o.w = pk2(s[6 * 33] * g1[2], s[7 * 33] * g1[3]);
;         const int wr_ = rowmap<MAP>(n0 + n), slot_ = PERMW ? ((wr_ & ~31) + invperm32(wr_ & 31)) : wr_;
;         *(u32x4*)((char*)WT + tiled_off(slot_, k0 + 8 * c, K / 64)) = o; }
; template <int MAP, bool HASG = false, bool PERMW = false>
; __device__ __forceinline__ void transpose_mat(const float* W, int K, int N, bf16_t* WT, LAS float* scr, int gw, int ngw, int lane, const float* gk = nullptr) {
;     const int nitems = (K / 64) * (N / 32);
;     int it = gw;
;     if (it >= nitems) return;
;     float wv[32];
;     tr_load(W, N, it, lane, wv);
.LBB0_826:
	s_cmpk_lt_u32 s2, 0x80
	s_cbranch_scc1 .Ltc2_done
	v_writelane_b32 v255, s4, 24
	v_writelane_b32 v255, s5, 25
	v_writelane_b32 v255, s6, 26
	v_writelane_b32 v255, s7, 27
	v_writelane_b32 v255, s8, 28
	v_writelane_b32 v255, s9, 29
	v_writelane_b32 v255, s10, 30
	v_writelane_b32 v255, s11, 31
	v_writelane_b32 v255, s12, 32
	v_writelane_b32 v255, s13, 33
	v_writelane_b32 v255, s14, 34
	v_writelane_b32 v255, s15, 35
	v_writelane_b32 v255, s16, 36
	v_writelane_b32 v255, s17, 37
	v_writelane_b32 v255, s18, 38
	v_writelane_b32 v255, s19, 39
	v_readlane_b32 s4, v254, 10
	v_readlane_b32 s5, v254, 11
	v_readfirstlane_b32 s8, v234
	s_nop 3
	s_and_b32 s6, s60, 0x2c00000
	s_add_u32 s4, s4, s6
	s_addc_u32 s5, s5, 0
	s_add_u32 s6, s76, 0xb600000
	s_addc_u32 s7, s77, 0
	s_lshr_b32 s8, s8, 6
	s_sub_u32 s9, s2, 0x80
	s_lshl_b32 s9, s9, 3
	s_add_u32 s9, s9, s8
	s_mul_i32 s10, s8, 0x2100
	v_and_b32_e32 v0, 63, v234
	v_and_b32_e32 v1, 31, v0
	v_lshrrev_b32_e32 v2, 5, v0
	v_lshlrev_b32_e32 v3, 13, v2
	v_lshl_add_u32 v3, v1, 2, v3
	v_mul_u32_u24_e32 v4, 33, v2
	v_add_u32_e32 v4, v4, v1
	v_lshl_add_u32 v4, v4, 2, s10
	v_and_b32_e32 v5, 7, v0
	v_lshrrev_b32_e32 v6, 3, v0
	v_mul_u32_u24_e32 v7, 0x108, v5
	v_add_u32_e32 v7, v7, v6
	v_lshl_add_u32 v7, v7, 2, s10
	v_lshrrev_b32_e32 v8, 2, v5
	v_lshlrev_b32_e32 v8, 10, v8
	v_and_b32_e32 v9, 3, v5
	v_lshlrev_b32_e32 v9, 4, v9
	v_lshl_add_u32 v8, v6, 6, v8
	v_add_u32_e32 v8, v8, v9
	v_xor_b32_e32 v9, 32, v8
	v_add_u32_e32 v9, 0x200, v9
